# f7 + GEMM phase prologues issue both LDS-DMA stage groups before the first wait
# baseline (speedup 1.0000x reference)
; #define PG8_STAGE(bufoff, gbase, voff) do { _Pragma("unroll") for (int _i = 0; _i < 2; ++_i) \
;         __builtin_amdgcn_global_load_lds((const unsigned*)((const char*)(gbase) + (voff)[_i]), (LAS unsigned*)(lds + (bufoff) + ldsw + _i * 8192), 16, 0, 0); } while (0)
; #define PG8_WAIT_V(n) asm volatile("s_waitcnt vmcnt(" #n ")" ::: "memory")
; #define PG8_BAR __builtin_amdgcn_s_barrier()
; #define PG8_STAGE(bufoff, gbase, voff) do { _Pragma("unroll") for (int _i = 0; _i < 2; ++_i) \
;         __builtin_amdgcn_global_load_lds((const unsigned*)((const char*)(gbase) + (voff)[_i]), (LAS unsigned*)(lds + (bufoff) + ldsw + _i * 8192), 16, 0, 0); } while (0)
; #define PG8_WAIT_V(n) asm volatile("s_waitcnt vmcnt(" #n ")" ::: "memory")
; #define PG8_BAR __builtin_amdgcn_s_barrier()
; template <class Epi, class Sched, bool ALIGN_EPI, bool SP2>
; __device__ __forceinline__ void gemm_phase(LAS unsigned char* lds, const int K, const Sched& S, const Epi& E) {
;     ...
;     if constexpr (SP2) {
;         PG8_STAGE(PG8_SB(0, 0), cB, voffB); PG8_STAGE(PG8_SB(0, 1), cB + hstep, voffB); PG8_STAGE(PG8_SA(0, 0), cA, voffA); PG8_STAGE(PG8_SA(0, 1), cA + hstep, voffA);
;         if (wr == 1) PG8_BAR;
;         PG8_WAIT_V(2); PG8_BAR;
;         PG8_STAGE(PG8_SB(1, 0), cB + kstep, voffB); PG8_STAGE(PG8_SA(1, 0), cA + kstep, voffA); PG8_STAGE(PG8_SB(1, 1), cB + hstep + kstep, voffB);
;         PG8_WAIT_V(6); PG8_BAR;
.LBB0_211:
	s_add_u32 s24, s34, 0x1600000
	s_addc_u32 s25, s35, 0
	s_add_u32 s26, s34, 0x108000
	s_mov_b64 s[38:39], 0x80
	s_addc_u32 s27, s35, 0
	s_and_b32 s7, s7, 3
	s_add_i32 m0, s73, 0x18000
	v_lshl_add_u64 v[8:9], v[8:9], 0, s[38:39]
	s_lshl_b32 s9, s6, 13
	s_lshl_b32 s60, s7, 5
	s_lshl_b32 s43, s7, 12
	global_load_lds_dwordx4 v[8:9], off
	v_lshl_add_u64 v[6:7], v[6:7], 0, s[38:39]
	s_add_i32 m0, s73, 0x1a000
	s_add_i32 s22, s73, 0x8000
	s_add_i32 s23, s73, 0xa000
	global_load_lds_dwordx4 v[6:7], off
	v_lshl_add_u64 v[2:3], v[2:3], 0, s[38:39]
	s_mov_b32 m0, s22
	s_add_u32 s4, s88, 0x80080
	global_load_lds_dwordx4 v[2:3], off
	v_lshl_add_u64 v[2:3], v[4:5], 0, s[38:39]
	s_mov_b32 m0, s23
	s_addc_u32 s5, s89, 0
	global_load_lds_dwordx4 v[2:3], off
	s_add_i32 m0, s73, 0x1c000
	v_lshl_add_u64 v[2:3], s[4:5], 0, v[146:147]
	global_load_lds_dwordx4 v[2:3], off
	v_lshl_add_u64 v[2:3], s[4:5], 0, v[152:153]
	s_add_i32 m0, s73, 0x1e000
	v_lshlrev_b32_e32 v4, 2, v205
	global_load_lds_dwordx4 v[2:3], off
	s_waitcnt vmcnt(8)
	s_barrier
	v_and_b32_e32 v2, 48, v0
	v_or_b32_e32 v3, v209, v2
	v_lshl_or_b32 v2, v205, 6, v2
	v_and_b32_e32 v4, 32, v4
	v_bitop3_b32 v216, s43, v3, v210 bitop3:0xf6
	v_lshlrev_b32_e32 v3, 9, v0
	v_bitop3_b32 v2, v2, s9, v4 bitop3:0xde
	v_and_b32_e32 v3, 0x30000, v3
	v_lshlrev_b32_e32 v4, 12, v202
	s_cmpk_lt_u32 s42, 0x100
	v_or3_b32 v3, v200, v3, v4
	v_lshl_or_b32 v215, s6, 6, v205
	s_cselect_b64 s[42:43], -1, 0
	s_lshl_b32 s6, s7, 2
	v_add_u32_e32 v154, v3, v201
	v_lshlrev_b32_e32 v3, 5, v203
	s_waitcnt vmcnt(6)
	s_add_i32 s6, s6, 0
	v_and_b32_e32 v3, 0x70000, v3
	s_add_i32 s6, s6, 0x20000
	v_mov_b32_e32 v157, 0
	v_or3_b32 v3, v200, v3, v4
	s_add_i32 s57, 0, 0x10000
	s_add_i32 s59, 0, 0x14000
	v_add_u32_e32 v221, 0, v2
	v_mbcnt_lo_u32_b32 v2, -1, 0
	v_cmp_eq_u32_e64 s[4:5], 0, v213
	v_lshlrev_b32_e32 v217, 5, v215
	v_writelane_b32 v252, s6, 21
	v_or_b32_e32 v218, s60, v204
	v_mov_b32_e32 v155, v157
	v_add_u32_e32 v158, v3, v201
	v_mov_b32_e32 v159, v157
	v_mov_b64_e32 v[160:161], 0x2bf
	v_add_u32_e32 v219, s57, v216
	v_add_u32_e32 v220, s59, v216
	s_mov_b32 s81, 0xbfb8aa3b
	s_mov_b32 s56, 0x3f317218
	s_mov_b32 s58, 0x3d800000
	s_lshl_b32 s6, s60, 2
	v_mbcnt_hi_u32_b32 v222, -1, v2
	s_mov_b32 s83, 0
	s_barrier
	v_writelane_b32 v252, s6, 22
	s_branch .LBB0_214

; #define PG8_STAGE(bufoff, gbase, voff) do { _Pragma("unroll") for (int _i = 0; _i < 2; ++_i) \
;         __builtin_amdgcn_global_load_lds((const unsigned*)((const char*)(gbase) + (voff)[_i]), (LAS unsigned*)(lds + (bufoff) + ldsw + _i * 8192), 16, 0, 0); } while (0)
; #define PG8_WAIT_V(n) asm volatile("s_waitcnt vmcnt(" #n ")" ::: "memory")
; #define PG8_BAR __builtin_amdgcn_s_barrier()
; #define PG8_STAGE(bufoff, gbase, voff) do { _Pragma("unroll") for (int _i = 0; _i < 2; ++_i) \
;         __builtin_amdgcn_global_load_lds((const unsigned*)((const char*)(gbase) + (voff)[_i]), (LAS unsigned*)(lds + (bufoff) + ldsw + _i * 8192), 16, 0, 0); } while (0)
; #define PG8_WAIT_V(n) asm volatile("s_waitcnt vmcnt(" #n ")" ::: "memory")
; #define PG8_BAR __builtin_amdgcn_s_barrier()
; template <class Epi, class Sched, bool ALIGN_EPI, bool SP2>
; __device__ __forceinline__ void gemm_phase8(LAS unsigned char* lds, const int K, const Sched& S, const Epi& E) {
;     ...
;     if constexpr (SP2) {
;         PG8_STAGE(PG8_SB(0, 0), cB, voffB); PG8_STAGE(PG8_SB(0, 1), cB + hstep, voffB); PG8_STAGE(PG8_SA(0, 0), cA, voffA); PG8_STAGE(PG8_SA(0, 1), cA + hstep, voffA);
;         if (wr == 1) PG8_BAR;
;         PG8_WAIT_V(2); PG8_BAR;
;         PG8_STAGE(PG8_SB(1, 0), cB + kstep, voffB); PG8_STAGE(PG8_SA(1, 0), cA + kstep, voffA); PG8_STAGE(PG8_SB(1, 1), cB + hstep + kstep, voffB);
;         PG8_WAIT_V(6); PG8_BAR;
.LBB0_474:
	s_lshl_b32 s5, s5, 5
	s_mov_b64 s[8:9], 0x80
	s_and_b32 s5, s5, 0x60
	s_add_i32 m0, s13, 0x18000
	v_lshl_add_u64 v[8:9], v[8:9], 0, s[8:9]
	s_lshl_b32 s1, s4, 13
	s_lshr_b32 s11, s5, 3
	global_load_lds_dwordx4 v[8:9], off
	v_lshl_add_u64 v[6:7], v[6:7], 0, s[8:9]
	s_add_i32 m0, s13, 0x1a000
	s_add_i32 s33, s13, 0x8000
	s_add_i32 s58, s13, 0xa000
	global_load_lds_dwordx4 v[6:7], off
	v_lshl_add_u64 v[2:3], v[2:3], 0, s[8:9]
	s_mov_b32 m0, s33
	s_add_u32 s26, s54, 0x40080
	global_load_lds_dwordx4 v[2:3], off
	v_lshl_add_u64 v[2:3], v[4:5], 0, s[8:9]
	s_mov_b32 m0, s58
	s_addc_u32 s27, s55, 0
	global_load_lds_dwordx4 v[2:3], off
	s_add_i32 m0, s13, 0x1c000
	v_lshl_add_u64 v[2:3], s[26:27], 0, v[164:165]
	global_load_lds_dwordx4 v[2:3], off
	v_lshl_add_u64 v[2:3], s[26:27], 0, v[168:169]
	s_add_i32 m0, s13, 0x1e000
	v_lshlrev_b32_e32 v4, 11, v202
	global_load_lds_dwordx4 v[2:3], off
	s_waitcnt vmcnt(8)
	s_barrier
	v_lshlrev_b32_e32 v3, 2, v205
	v_lshlrev_b32_e32 v2, 6, v205
	v_and_b32_e32 v3, 32, v3
	v_bitop3_b32 v2, v2, v3, v189 bitop3:0x36
	v_or_b32_e32 v3, s11, v188
	v_lshl_or_b32 v194, v3, 10, v191
	v_lshlrev_b32_e32 v3, 8, v0
	v_and_b32_e32 v3, 0x18000, v3
	v_or3_b32 v3, v200, v3, v4
	v_add_u32_e32 v172, v3, v201
	v_lshlrev_b32_e32 v3, 4, v203
	s_waitcnt vmcnt(6)
	s_cmpk_lt_u32 s10, 0x100
	v_and_b32_e32 v3, 0x38000, v3
	v_or3_b32 v2, v2, s1, v190
	s_cselect_b64 s[10:11], -1, 0
	v_or3_b32 v3, v200, v3, v4
	s_add_i32 s59, 0, 0x10000
	s_add_i32 s60, 0, 0x14000
	v_lshl_or_b32 v193, s4, 6, v205
	v_or_b32_e32 v195, s5, v204
	v_mov_b32_e32 v173, v171
	v_add_u32_e32 v174, v3, v201
	v_mov_b32_e32 v175, v171
	v_mov_b64_e32 v[176:177], 0x100
	v_mov_b64_e32 v[178:179], 0xff
	v_add_u32_e32 v196, s59, v194
	v_add_u32_e32 v197, s60, v194
	v_add_u32_e32 v198, 0, v2
	s_movk_i32 s61, 0x1800
	s_mov_b32 s62, 0xbfb8aa3b
	s_mov_b32 s63, 0x437f0000
	s_mov_b32 s22, 0x3f317218
	s_mov_b32 s24, 0x3d800000
	s_movk_i32 s72, 0x3c00
	s_barrier
	s_branch .LBB0_477

; #define PG8_STAGE(bufoff, gbase, voff) do { _Pragma("unroll") for (int _i = 0; _i < 2; ++_i) \
;         __builtin_amdgcn_global_load_lds((const unsigned*)((const char*)(gbase) + (voff)[_i]), (LAS unsigned*)(lds + (bufoff) + ldsw + _i * 8192), 16, 0, 0); } while (0)
; #define PG8_WAIT_V(n) asm volatile("s_waitcnt vmcnt(" #n ")" ::: "memory")
; #define PG8_BAR __builtin_amdgcn_s_barrier()
; #define PG8_STAGE(bufoff, gbase, voff) do { _Pragma("unroll") for (int _i = 0; _i < 2; ++_i) \
;         __builtin_amdgcn_global_load_lds((const unsigned*)((const char*)(gbase) + (voff)[_i]), (LAS unsigned*)(lds + (bufoff) + ldsw + _i * 8192), 16, 0, 0); } while (0)
; #define PG8_WAIT_V(n) asm volatile("s_waitcnt vmcnt(" #n ")" ::: "memory")
; #define PG8_BAR __builtin_amdgcn_s_barrier()
; template <class Epi, class Sched, bool ALIGN_EPI, bool SP2>
; __device__ __forceinline__ void gemm_phase8(LAS unsigned char* lds, const int K, const Sched& S, const Epi& E) {
;     ...
;     if constexpr (SP2) {
;         PG8_STAGE(PG8_SB(0, 0), cB, voffB); PG8_STAGE(PG8_SB(0, 1), cB + hstep, voffB); PG8_STAGE(PG8_SA(0, 0), cA, voffA); PG8_STAGE(PG8_SA(0, 1), cA + hstep, voffA);
;         if (wr == 1) PG8_BAR;
;         PG8_WAIT_V(2); PG8_BAR;
;         PG8_STAGE(PG8_SB(1, 0), cB + kstep, voffB); PG8_STAGE(PG8_SA(1, 0), cA + kstep, voffA); PG8_STAGE(PG8_SB(1, 1), cB + hstep + kstep, voffB);
;         PG8_WAIT_V(6); PG8_BAR;
.LBB0_561:
	s_lshl_b32 s5, s5, 5
	s_mov_b64 s[8:9], 0x80
	s_and_b32 s5, s5, 0x60
	s_add_i32 m0, s13, 0x18000
	v_lshl_add_u64 v[8:9], v[8:9], 0, s[8:9]
	s_lshl_b32 s1, s4, 13
	s_lshr_b32 s11, s5, 3
	global_load_lds_dwordx4 v[8:9], off
	v_lshl_add_u64 v[6:7], v[6:7], 0, s[8:9]
	s_add_i32 m0, s13, 0x1a000
	s_add_i32 s33, s13, 0x8000
	s_add_i32 s58, s13, 0xa000
	global_load_lds_dwordx4 v[6:7], off
	v_lshl_add_u64 v[2:3], v[2:3], 0, s[8:9]
	s_mov_b32 m0, s33
	s_add_u32 s26, s54, 0x40080
	global_load_lds_dwordx4 v[2:3], off
	v_lshl_add_u64 v[2:3], v[4:5], 0, s[8:9]
	s_mov_b32 m0, s58
	s_addc_u32 s27, s55, 0
	global_load_lds_dwordx4 v[2:3], off
	s_add_i32 m0, s13, 0x1c000
	v_lshl_add_u64 v[2:3], s[26:27], 0, v[164:165]
	global_load_lds_dwordx4 v[2:3], off
	v_lshl_add_u64 v[2:3], s[26:27], 0, v[168:169]
	s_add_i32 m0, s13, 0x1e000
	v_lshlrev_b32_e32 v4, 11, v202
	global_load_lds_dwordx4 v[2:3], off
	s_waitcnt vmcnt(8)
	s_barrier
	v_lshlrev_b32_e32 v3, 2, v205
	v_lshlrev_b32_e32 v2, 6, v205
	v_and_b32_e32 v3, 32, v3
	v_bitop3_b32 v2, v2, v3, v189 bitop3:0x36
	v_or_b32_e32 v3, s11, v188
	v_lshl_or_b32 v188, v3, 10, v191
	v_lshlrev_b32_e32 v3, 8, v0
	v_and_b32_e32 v3, 0x18000, v3
	v_or3_b32 v3, v200, v3, v4
	v_add_u32_e32 v172, v3, v201
	v_lshlrev_b32_e32 v3, 4, v203
	s_waitcnt vmcnt(6)
	s_cmpk_lt_u32 s10, 0x100
	v_and_b32_e32 v3, 0x38000, v3
	v_or3_b32 v2, v2, s1, v190
	s_cselect_b64 s[10:11], -1, 0
	v_or3_b32 v3, v200, v3, v4
	s_add_i32 s60, 0, 0x10000
	s_add_i32 s61, 0, 0x14000
	v_lshl_or_b32 v193, s4, 6, v205
	v_or_b32_e32 v189, s5, v204
	v_mov_b32_e32 v173, v171
	v_add_u32_e32 v174, v3, v201
	v_mov_b32_e32 v175, v171
	v_mov_b64_e32 v[176:177], 0x300
	v_mov_b64_e32 v[178:179], 0x2ff
	s_movk_i32 s59, 0x61
	v_add_u32_e32 v190, s60, v188
	v_add_u32_e32 v191, s61, v188
	v_add_u32_e32 v194, 0, v2
	s_movk_i32 s62, 0x1800
	s_mov_b32 s63, 0xbfb8aa3b
	s_mov_b32 s72, 0x437f0000
	s_mov_b32 s22, 0x3f317218
	s_mov_b32 s24, 0x3d800000
	s_movk_i32 s73, 0x3c00
	s_barrier
	s_branch .LBB0_564

;     __device__ __forceinline__ const char* aptr(const Unit& u) const { return (u.sub ? A2 : A) + (size_t)u.pm * tstep; }
;     __device__ __forceinline__ const char* bptr(const Unit& u) const { return (u.sub ? B2 : B) + (size_t)u.pn * tstep; }
;     __device__ __forceinline__ const char* aptr(const Unit& u) const { return (u.sub == 2 ? A2 : A + (size_t)u.sub * astride) + (size_t)u.pm * tstep; }
; #define PG8_STAGE(bufoff, gbase, voff) do { _Pragma("unroll") for (int _i = 0; _i < 2; ++_i) \
;         __builtin_amdgcn_global_load_lds((const unsigned*)((const char*)(gbase) + (voff)[_i]), (LAS unsigned*)(lds + (bufoff) + ldsw + _i * 8192), 16, 0, 0); } while (0)
; #define PG8_WAIT_V(n) asm volatile("s_waitcnt vmcnt(" #n ")" ::: "memory")
; #define PG8_BAR __builtin_amdgcn_s_barrier()
; #define PG8_STAGE(bufoff, gbase, voff) do { _Pragma("unroll") for (int _i = 0; _i < 2; ++_i) \
;         __builtin_amdgcn_global_load_lds((const unsigned*)((const char*)(gbase) + (voff)[_i]), (LAS unsigned*)(lds + (bufoff) + ldsw + _i * 8192), 16, 0, 0); } while (0)
; #define PG8_WAIT_V(n) asm volatile("s_waitcnt vmcnt(" #n ")" ::: "memory")
; #define PG8_BAR __builtin_amdgcn_s_barrier()
; template <class Epi, class Sched, bool ALIGN_EPI, bool SP2>
; __device__ __forceinline__ void gemm_phase(LAS unsigned char* lds, const int K, const Sched& S, const Epi& E) {
;     ...
;     Acc acc;
; #pragma unroll
;     for (int a = 0; a < 2; ++a)
; #pragma unroll
;         for (int b = 0; b < 2; ++b)
; #pragma unroll
;             for (int m = 0; m < 4; ++m)
; #pragma unroll
;                 for (int n = 0; n < 2; ++n) acc[a][b][m][n] = (f32x4){0.f, 0.f, 0.f, 0.f};
;     bf16x8 At[4][2], B0[2][2], B1[2][2];
;     const char* cA = S.aptr(cur); const char* cB = S.bptr(cur);
;     if constexpr (SP2) {
;         PG8_STAGE(PG8_SB(0, 0), cB, voffB); PG8_STAGE(PG8_SB(0, 1), cB + hstep, voffB); PG8_STAGE(PG8_SA(0, 0), cA, voffA); PG8_STAGE(PG8_SA(0, 1), cA + hstep, voffA);
;         if (wr == 1) PG8_BAR;
;         PG8_WAIT_V(2); PG8_BAR;
;         PG8_STAGE(PG8_SB(1, 0), cB + kstep, voffB); PG8_STAGE(PG8_SA(1, 0), cA + kstep, voffA); PG8_STAGE(PG8_SB(1, 1), cB + hstep + kstep, voffB);
;         PG8_WAIT_V(6); PG8_BAR;
.LBB0_858:
	s_add_u32 s47, s34, 0x12800000
	s_addc_u32 s48, s35, 0
	s_add_u32 s10, s34, 0xf800000
	s_addc_u32 s11, s35, 0
	s_add_u32 s16, s34, 0xc000000
	s_addc_u32 s17, s35, 0
	s_lshl_b32 s1, s1, 5
	s_mov_b64 s[18:19], 0x80
	s_and_b32 s1, s1, 0x60
	s_add_i32 m0, s15, 0x18000
	v_lshl_add_u64 v[8:9], v[8:9], 0, s[18:19]
	s_ashr_i32 s49, s2, 31
	s_lshl_b32 s5, s0, 13
	s_lshl_b32 s22, s1, 7
	global_load_lds_dwordx4 v[8:9], off
	v_lshl_add_u64 v[6:7], v[6:7], 0, s[18:19]
	s_add_i32 m0, s15, 0x1a000
	s_add_i32 s50, s15, 0x8000
	s_add_i32 s51, s15, 0xa000
	global_load_lds_dwordx4 v[6:7], off
	v_lshl_add_u64 v[2:3], v[2:3], 0, s[18:19]
	s_mov_b32 m0, s50
	s_add_u32 s20, s42, 0x40080
	global_load_lds_dwordx4 v[2:3], off
	v_lshl_add_u64 v[2:3], v[4:5], 0, s[18:19]
	s_mov_b32 m0, s51
	s_addc_u32 s21, s43, 0
	global_load_lds_dwordx4 v[2:3], off
	s_add_i32 m0, s15, 0x1c000
	v_lshl_add_u64 v[2:3], s[20:21], 0, v[176:177]
	global_load_lds_dwordx4 v[2:3], off
	v_lshl_add_u64 v[2:3], s[20:21], 0, v[180:181]
	s_add_i32 m0, s15, 0x1e000
	v_lshlrev_b32_e32 v4, 6, v0
	global_load_lds_dwordx4 v[2:3], off
	s_waitcnt vmcnt(8)
	s_barrier
	v_and_b32_e32 v2, 15, v0
	v_lshlrev_b32_e32 v3, 1, v14
	s_movk_i32 s20, 0x3c0
	v_lshlrev_b32_e32 v5, 2, v0
	v_and_or_b32 v4, v4, s20, v3
	v_and_b32_e32 v5, 32, v5
	v_lshl_or_b32 v206, s0, 6, v2
	v_lshl_or_b32 v2, v2, 6, v3
	v_lshlrev_b32_e32 v3, 8, v0
	v_bitop3_b32 v207, s22, v4, v5 bitop3:0xf6
	v_and_b32_e32 v3, 0x18000, v3
	v_lshlrev_b32_e32 v4, 11, v13
	v_or3_b32 v3, v11, v3, v4
	v_add_u32_e32 v182, v3, v12
	v_lshlrev_b32_e32 v3, 4, v15
	v_and_b32_e32 v3, 0x38000, v3
	v_or3_b32 v3, v11, v3, v4
	s_waitcnt vmcnt(6)
	v_add_u32_e32 v184, v3, v12
	v_mov_b32_e32 v12, v10
	v_mov_b32_e32 v13, v10
	v_bitop3_b32 v2, v2, s5, v5 bitop3:0xde
	s_cmpk_lt_u32 s4, 0x100
	v_or_b32_e32 v208, s1, v14
	v_mov_b32_e32 v11, v10
	v_mov_b64_e32 v[16:17], v[12:13]
	v_mov_b64_e32 v[20:21], v[12:13]
	v_mov_b64_e32 v[32:33], v[12:13]
	v_mov_b64_e32 v[36:37], v[12:13]
	v_mov_b64_e32 v[56:57], v[12:13]
	v_mov_b64_e32 v[60:61], v[12:13]
	v_mov_b64_e32 v[88:89], v[12:13]
	v_mov_b64_e32 v[92:93], v[12:13]
	v_mov_b64_e32 v[24:25], v[12:13]
	v_mov_b64_e32 v[28:29], v[12:13]
	v_mov_b64_e32 v[40:41], v[12:13]
	v_mov_b64_e32 v[44:45], v[12:13]
	v_mov_b64_e32 v[72:73], v[12:13]
	v_mov_b64_e32 v[76:77], v[12:13]
	v_mov_b64_e32 v[104:105], v[12:13]
	v_mov_b64_e32 v[108:109], v[12:13]
	v_mov_b64_e32 v[120:121], v[12:13]
	v_mov_b64_e32 v[124:125], v[12:13]
	v_mov_b64_e32 v[152:153], v[12:13]
	v_mov_b64_e32 v[156:157], v[12:13]
	v_mov_b64_e32 v[160:161], v[12:13]
	v_mov_b64_e32 v[164:165], v[12:13]
	v_mov_b64_e32 v[168:169], v[12:13]
	v_mov_b64_e32 v[172:173], v[12:13]
	v_mov_b64_e32 v[136:137], v[12:13]
	v_mov_b64_e32 v[140:141], v[12:13]
	v_mov_b64_e32 v[128:129], v[12:13]
	v_mov_b64_e32 v[132:133], v[12:13]
	v_mov_b64_e32 v[96:97], v[12:13]
	v_mov_b64_e32 v[100:101], v[12:13]
	v_mov_b64_e32 v[64:65], v[12:13]
	v_mov_b64_e32 v[68:69], v[12:13]
	s_cselect_b64 s[20:21], -1, 0
	v_mov_b32_e32 v183, v10
	v_mov_b32_e32 v185, v10
	s_mov_b32 s39, 0
	v_mov_b64_e32 v[186:187], 0x100
	v_mov_b64_e32 v[188:189], 0xff
	s_add_i32 s52, 0, 0x10000
	s_add_i32 s53, 0, 0x14000
	v_add_u32_e32 v209, 0, v2
	s_movk_i32 s54, 0x1800
	s_mov_b32 s22, 0x3b808081
	v_mov_b64_e32 v[14:15], v[10:11]
	v_mov_b64_e32 v[18:19], v[10:11]
	v_mov_b64_e32 v[30:31], v[10:11]
	v_mov_b64_e32 v[34:35], v[10:11]
	v_mov_b64_e32 v[54:55], v[10:11]
	v_mov_b64_e32 v[58:59], v[10:11]
	v_mov_b64_e32 v[86:87], v[10:11]
	v_mov_b64_e32 v[90:91], v[10:11]
	v_mov_b64_e32 v[22:23], v[10:11]
	v_mov_b64_e32 v[26:27], v[10:11]
	v_mov_b64_e32 v[38:39], v[10:11]
	v_mov_b64_e32 v[42:43], v[10:11]
	v_mov_b64_e32 v[70:71], v[10:11]
	v_mov_b64_e32 v[74:75], v[10:11]
	v_mov_b64_e32 v[102:103], v[10:11]
	v_mov_b64_e32 v[106:107], v[10:11]
	v_mov_b64_e32 v[118:119], v[10:11]
	v_mov_b64_e32 v[122:123], v[10:11]
	v_mov_b64_e32 v[150:151], v[10:11]
	v_mov_b64_e32 v[154:155], v[10:11]
	v_mov_b64_e32 v[158:159], v[10:11]
	v_mov_b64_e32 v[162:163], v[10:11]
	v_mov_b64_e32 v[166:167], v[10:11]
	v_mov_b64_e32 v[170:171], v[10:11]
	v_mov_b64_e32 v[134:135], v[10:11]
	v_mov_b64_e32 v[138:139], v[10:11]
	v_mov_b64_e32 v[126:127], v[10:11]
	v_mov_b64_e32 v[130:131], v[10:11]
	v_mov_b64_e32 v[94:95], v[10:11]
	v_mov_b64_e32 v[98:99], v[10:11]
	v_mov_b64_e32 v[62:63], v[10:11]
	v_mov_b64_e32 v[66:67], v[10:11]
	s_mov_b32 s55, 0
	s_barrier
	s_branch .LBB0_861

;     __device__ __forceinline__ const char* aptr(const Unit& u) const { return (u.sub ? A2 : A) + (size_t)u.pm * tstep; }
;     __device__ __forceinline__ const char* bptr(const Unit& u) const { return (u.sub ? B2 : B) + (size_t)u.pn * tstep; }
;     __device__ __forceinline__ const char* aptr(const Unit& u) const { return (u.sub == 2 ? A2 : A + (size_t)u.sub * astride) + (size_t)u.pm * tstep; }
; #define PG8_STAGE(bufoff, gbase, voff) do { _Pragma("unroll") for (int _i = 0; _i < 2; ++_i) \
;         __builtin_amdgcn_global_load_lds((const unsigned*)((const char*)(gbase) + (voff)[_i]), (LAS unsigned*)(lds + (bufoff) + ldsw + _i * 8192), 16, 0, 0); } while (0)
; #define PG8_WAIT_V(n) asm volatile("s_waitcnt vmcnt(" #n ")" ::: "memory")
; #define PG8_BAR __builtin_amdgcn_s_barrier()
; #define PG8_WAIT_V(n) asm volatile("s_waitcnt vmcnt(" #n ")" ::: "memory")
; #define PG8_BAR __builtin_amdgcn_s_barrier()
; template <class Epi, class Sched, bool ALIGN_EPI, bool SP2>
; __device__ __forceinline__ void gemm_phase(LAS unsigned char* lds, const int K, const Sched& S, const Epi& E) {
;     ...
;     Acc acc;
; #pragma unroll
;     for (int a = 0; a < 2; ++a)
; #pragma unroll
;         for (int b = 0; b < 2; ++b)
; #pragma unroll
;             for (int m = 0; m < 4; ++m)
; #pragma unroll
;                 for (int n = 0; n < 2; ++n) acc[a][b][m][n] = (f32x4){0.f, 0.f, 0.f, 0.f};
;     bf16x8 At[4][2], B0[2][2], B1[2][2];
;     const char* cA = S.aptr(cur); const char* cB = S.bptr(cur);
;     if constexpr (SP2) {
;         PG8_STAGE(PG8_SB(0, 0), cB, voffB); PG8_STAGE(PG8_SB(0, 1), cB + hstep, voffB); PG8_STAGE(PG8_SA(0, 0), cA, voffA); PG8_STAGE(PG8_SA(0, 1), cA + hstep, voffA);
;         if (wr == 1) PG8_BAR;
;         PG8_WAIT_V(2); PG8_BAR;
;         PG8_STAGE(PG8_SB(1, 0), cB + kstep, voffB); PG8_STAGE(PG8_SA(1, 0), cA + kstep, voffA); PG8_STAGE(PG8_SB(1, 1), cB + hstep + kstep, voffB);
;         PG8_WAIT_V(6); PG8_BAR;
;     } else {
;         PG8_STAGE(PG8_SB(0, 0), cB, voffB); PG8_STAGE(PG8_SA(0, 0), cA, voffA); PG8_STAGE(PG8_SB(0, 1), cB + hstep, voffB); PG8_STAGE(PG8_SA(0, 1), cA + hstep, voffA);
;         if (wr == 1) PG8_BAR;
;         PG8_WAIT_V(4); PG8_BAR;
;         PG8_STAGE(PG8_SB(1, 0), cB + kstep, voffB); PG8_STAGE(PG8_SA(1, 0), cA + kstep, voffA); PG8_STAGE(PG8_SB(1, 1), cB + hstep + kstep, voffB);
;         PG8_WAIT_V(6); PG8_BAR;
;     }
.LBB0_1017:
	s_sext_i32_i8 s8, s0
	v_and_b32_e32 v152, 15, v0
	v_and_b32_e32 v14, 48, v0
	v_lshlrev_b32_e32 v15, 6, v0
	s_movk_i32 s0, 0x3c0
	v_lshlrev_b32_e32 v16, 2, v0
	s_mov_b64 s[18:19], 0x80
	v_and_or_b32 v15, v15, s0, v14
	v_and_b32_e32 v16, 32, v16
	s_and_b32 s39, s4, 3
	s_lshl_b32 s0, s1, 13
	v_lshl_or_b32 v14, v152, 6, v14
	s_add_i32 m0, s11, 0x18000
	v_lshl_add_u64 v[8:9], v[8:9], 0, s[18:19]
	s_lshl_b32 s44, s1, 6
	v_bitop3_b32 v14, v14, s0, v16 bitop3:0xde
	s_lshl_b32 s0, s39, 12
	global_load_lds_dwordx4 v[8:9], off
	v_lshl_add_u64 v[6:7], v[6:7], 0, s[18:19]
	s_add_i32 m0, s11, 0x1a000
	s_add_i32 s45, s11, 0x8000
	s_add_i32 s46, s11, 0xa000
	global_load_lds_dwordx4 v[6:7], off
	v_lshl_add_u64 v[4:5], v[4:5], 0, s[18:19]
	s_mov_b32 m0, s45
	s_add_u32 s4, s28, 0x80080
	global_load_lds_dwordx4 v[4:5], off
	v_lshl_add_u64 v[2:3], v[2:3], 0, s[18:19]
	s_mov_b32 m0, s46
	s_addc_u32 s5, s29, 0
	global_load_lds_dwordx4 v[2:3], off
	s_add_i32 m0, s11, 0x1c000
	v_lshl_add_u64 v[2:3], s[4:5], 0, v[132:133]
	global_load_lds_dwordx4 v[2:3], off
	v_lshl_add_u64 v[2:3], s[4:5], 0, v[136:137]
	s_add_i32 m0, s11, 0x1e000
	v_lshlrev_b32_e32 v4, 12, v12
	global_load_lds_dwordx4 v[2:3], off
	s_waitcnt vmcnt(8)
	s_barrier
	v_lshlrev_b32_e32 v2, 9, v0
	v_and_b32_e32 v2, 0x30000, v2
	v_or3_b32 v2, v10, v2, v4
	v_bitop3_b32 v153, s0, v15, v16 bitop3:0xf6
	s_mov_b64 s[0:1], 0x80080
	v_add_u32_e32 v2, v2, v11
	v_mov_b32_e32 v3, v133
	v_lshl_add_u64 v[138:139], v[2:3], 0, s[0:1]
	v_lshlrev_b32_e32 v2, 5, v13
	v_and_b32_e32 v2, 0x70000, v2
	s_waitcnt vmcnt(6)
	v_or3_b32 v2, v10, v2, v4
	v_add_u32_e32 v2, v2, v11
	v_or_b32_e32 v150, s44, v152
	v_lshl_add_u64 v[140:141], v[2:3], 0, s[0:1]
	v_mov_b64_e32 v[142:143], 0x100
	v_mov_b64_e32 v[144:145], 0xff
	s_add_i32 s47, 0, 0x10000
	s_add_i32 s48, 0, 0x14000
	v_add_u32_e32 v154, 0, v14
	v_mov_b32_e32 v2, v133
	v_mov_b32_e32 v4, v133
	v_mov_b32_e32 v5, v133
	v_mov_b32_e32 v6, v133
	v_mov_b32_e32 v7, v133
	v_mov_b32_e32 v8, v133
	v_mov_b32_e32 v9, v133
	v_mov_b32_e32 v18, v133
	v_mov_b32_e32 v19, v133
	v_mov_b32_e32 v20, v133
	v_mov_b32_e32 v21, v133
	v_mov_b32_e32 v22, v133
	v_mov_b32_e32 v23, v133
	v_mov_b32_e32 v24, v133
	v_mov_b32_e32 v25, v133
	v_mov_b32_e32 v34, v133
	v_mov_b32_e32 v35, v133
	v_mov_b32_e32 v36, v133
	v_mov_b32_e32 v37, v133
	v_mov_b32_e32 v38, v133
	v_mov_b32_e32 v39, v133
	v_mov_b32_e32 v40, v133
	v_mov_b32_e32 v41, v133
	v_mov_b32_e32 v50, v133
	v_mov_b32_e32 v51, v133
	v_mov_b32_e32 v52, v133
	v_mov_b32_e32 v53, v133
	v_mov_b32_e32 v54, v133
	v_mov_b32_e32 v55, v133
	v_mov_b32_e32 v56, v133
	v_mov_b32_e32 v57, v133
	v_mov_b32_e32 v10, v133
	v_mov_b32_e32 v11, v133
	v_mov_b32_e32 v12, v133
	v_mov_b32_e32 v13, v133
	v_mov_b32_e32 v14, v133
	v_mov_b32_e32 v15, v133
	v_mov_b32_e32 v16, v133
	v_mov_b32_e32 v17, v133
	v_mov_b32_e32 v26, v133
	v_mov_b32_e32 v27, v133
	v_mov_b32_e32 v28, v133
	v_mov_b32_e32 v29, v133
	v_mov_b32_e32 v30, v133
	v_mov_b32_e32 v31, v133
	v_mov_b32_e32 v32, v133
	v_mov_b32_e32 v33, v133
	v_mov_b32_e32 v42, v133
	v_mov_b32_e32 v43, v133
	v_mov_b32_e32 v44, v133
	v_mov_b32_e32 v45, v133
	v_mov_b32_e32 v46, v133
	v_mov_b32_e32 v47, v133
	v_mov_b32_e32 v48, v133
	v_mov_b32_e32 v49, v133
	v_mov_b32_e32 v58, v133
	v_mov_b32_e32 v59, v133
	v_mov_b32_e32 v60, v133
	v_mov_b32_e32 v61, v133
	v_mov_b32_e32 v62, v133
	v_mov_b32_e32 v63, v133
	v_mov_b32_e32 v64, v133
	v_mov_b32_e32 v65, v133
	v_mov_b32_e32 v66, v133
	v_mov_b32_e32 v67, v133
	v_mov_b32_e32 v68, v133
	v_mov_b32_e32 v69, v133
	v_mov_b32_e32 v70, v133
	v_mov_b32_e32 v71, v133
	v_mov_b32_e32 v72, v133
	v_mov_b32_e32 v73, v133
	v_mov_b32_e32 v82, v133
	v_mov_b32_e32 v83, v133
	v_mov_b32_e32 v84, v133
	v_mov_b32_e32 v85, v133
	v_mov_b32_e32 v86, v133
	v_mov_b32_e32 v87, v133
	v_mov_b32_e32 v88, v133
	v_mov_b32_e32 v89, v133
	v_mov_b32_e32 v98, v133
	v_mov_b32_e32 v99, v133
	v_mov_b32_e32 v100, v133
	v_mov_b32_e32 v101, v133
	v_mov_b32_e32 v102, v133
	v_mov_b32_e32 v103, v133
	v_mov_b32_e32 v104, v133
	v_mov_b32_e32 v105, v133
	v_mov_b32_e32 v114, v133
	v_mov_b32_e32 v115, v133
	v_mov_b32_e32 v116, v133
	v_mov_b32_e32 v117, v133
	v_mov_b32_e32 v118, v133
	v_mov_b32_e32 v119, v133
	v_mov_b32_e32 v120, v133
	v_mov_b32_e32 v121, v133
	v_mov_b32_e32 v74, v133
	v_mov_b32_e32 v75, v133
	v_mov_b32_e32 v76, v133
	v_mov_b32_e32 v77, v133
	v_mov_b32_e32 v78, v133
	v_mov_b32_e32 v79, v133
	v_mov_b32_e32 v80, v133
	v_mov_b32_e32 v81, v133
	v_mov_b32_e32 v90, v133
	v_mov_b32_e32 v91, v133
	v_mov_b32_e32 v92, v133
	v_mov_b32_e32 v93, v133
	v_mov_b32_e32 v94, v133
	v_mov_b32_e32 v95, v133
	v_mov_b32_e32 v96, v133
	v_mov_b32_e32 v97, v133
	v_mov_b32_e32 v106, v133
	v_mov_b32_e32 v107, v133
	v_mov_b32_e32 v108, v133
	v_mov_b32_e32 v109, v133
	v_mov_b32_e32 v110, v133
	v_mov_b32_e32 v111, v133
	v_mov_b32_e32 v112, v133
	v_mov_b32_e32 v113, v133
	v_mov_b32_e32 v122, v133
	v_mov_b32_e32 v123, v133
	v_mov_b32_e32 v124, v133
	v_mov_b32_e32 v125, v133
	v_mov_b32_e32 v126, v133
	v_mov_b32_e32 v127, v133
	v_mov_b32_e32 v128, v133
	v_mov_b32_e32 v129, v133
	s_barrier
	s_branch .LBB0_1020

;     __device__ __forceinline__ const char* aptr(const Unit& u) const { return (u.sub ? A2 : A) + (size_t)u.pm * tstep; }
;     __device__ __forceinline__ const char* bptr(const Unit& u) const { return (u.sub ? B2 : B) + (size_t)u.pn * tstep; }
;     __device__ __forceinline__ const char* aptr(const Unit& u) const { return (u.sub == 2 ? A2 : A + (size_t)u.sub * astride) + (size_t)u.pm * tstep; }
; #define PG8_STAGE(bufoff, gbase, voff) do { _Pragma("unroll") for (int _i = 0; _i < 2; ++_i) \
;         __builtin_amdgcn_global_load_lds((const unsigned*)((const char*)(gbase) + (voff)[_i]), (LAS unsigned*)(lds + (bufoff) + ldsw + _i * 8192), 16, 0, 0); } while (0)
; #define PG8_WAIT_V(n) asm volatile("s_waitcnt vmcnt(" #n ")" ::: "memory")
; #define PG8_BAR __builtin_amdgcn_s_barrier()
; #define PG8_STAGE(bufoff, gbase, voff) do { _Pragma("unroll") for (int _i = 0; _i < 2; ++_i) \
;         __builtin_amdgcn_global_load_lds((const unsigned*)((const char*)(gbase) + (voff)[_i]), (LAS unsigned*)(lds + (bufoff) + ldsw + _i * 8192), 16, 0, 0); } while (0)
; #define PG8_WAIT_V(n) asm volatile("s_waitcnt vmcnt(" #n ")" ::: "memory")
; #define PG8_BAR __builtin_amdgcn_s_barrier()
; template <class Epi, class Sched, bool ALIGN_EPI, bool SP2>
; __device__ __forceinline__ void gemm_phase(LAS unsigned char* lds, const int K, const Sched& S, const Epi& E) {
;     ...
;     Acc acc;
; #pragma unroll
;     for (int a = 0; a < 2; ++a)
; #pragma unroll
;         for (int b = 0; b < 2; ++b)
; #pragma unroll
;             for (int m = 0; m < 4; ++m)
; #pragma unroll
;                 for (int n = 0; n < 2; ++n) acc[a][b][m][n] = (f32x4){0.f, 0.f, 0.f, 0.f};
;     bf16x8 At[4][2], B0[2][2], B1[2][2];
;     const char* cA = S.aptr(cur); const char* cB = S.bptr(cur);
;     if constexpr (SP2) {
;         PG8_STAGE(PG8_SB(0, 0), cB, voffB); PG8_STAGE(PG8_SB(0, 1), cB + hstep, voffB); PG8_STAGE(PG8_SA(0, 0), cA, voffA); PG8_STAGE(PG8_SA(0, 1), cA + hstep, voffA);
;         if (wr == 1) PG8_BAR;
;         PG8_WAIT_V(2); PG8_BAR;
;         PG8_STAGE(PG8_SB(1, 0), cB + kstep, voffB); PG8_STAGE(PG8_SA(1, 0), cA + kstep, voffA); PG8_STAGE(PG8_SB(1, 1), cB + hstep + kstep, voffB);
;         PG8_WAIT_V(6); PG8_BAR;
.LBB0_1098:
	s_add_u32 s8, s34, 0x8000000
	s_addc_u32 s9, s35, 0
	s_lshl_b32 s10, s10, 5
	s_and_b32 s20, s10, 0x60
	s_mov_b64 s[10:11], 0x80
	s_add_i32 m0, s27, 0x18000
	v_lshl_add_u64 v[8:9], v[8:9], 0, s[10:11]
	s_lshl_b32 s17, s16, 13
	s_lshl_b32 s21, s20, 7
	global_load_lds_dwordx4 v[8:9], off
	v_lshl_add_u64 v[6:7], v[6:7], 0, s[10:11]
	s_add_i32 m0, s27, 0x1a000
	s_add_i32 s42, s27, 0x8000
	s_add_i32 s43, s27, 0xa000
	global_load_lds_dwordx4 v[6:7], off
	v_lshl_add_u64 v[2:3], v[2:3], 0, s[10:11]
	s_mov_b32 m0, s42
	s_add_u32 s18, s30, 0x80080
	global_load_lds_dwordx4 v[2:3], off
	v_lshl_add_u64 v[2:3], v[4:5], 0, s[10:11]
	s_mov_b32 m0, s43
	s_addc_u32 s19, s31, 0
	global_load_lds_dwordx4 v[2:3], off
	s_add_i32 m0, s27, 0x1c000
	v_lshl_add_u64 v[2:3], s[18:19], 0, v[134:135]
	global_load_lds_dwordx4 v[2:3], off
	v_lshl_add_u64 v[2:3], s[18:19], 0, v[130:131]
	s_add_i32 m0, s27, 0x1e000
	s_sext_i32_i16 s50, s0
	global_load_lds_dwordx4 v[2:3], off
	s_waitcnt vmcnt(8)
	s_barrier
	v_and_b32_e32 v2, 15, v0
	v_lshlrev_b32_e32 v3, 1, v14
	v_lshl_or_b32 v152, s16, 6, v2
	v_lshl_or_b32 v4, v2, 6, v3
	v_lshlrev_b32_e32 v2, 2, v2
	v_and_b32_e32 v5, 32, v2
	v_bitop3_b32 v4, v4, s17, v5 bitop3:0xde
	v_lshlrev_b32_e32 v5, 6, v0
	s_movk_i32 s0, 0x3c0
	v_and_or_b32 v3, v5, s0, v3
	s_lshl_b32 s0, s16, 8
	s_add_i32 s0, s0, 0
	s_add_i32 s0, s0, 0x20000
	v_and_b32_e32 v5, 32, v10
	v_add_u32_e32 v154, s0, v2
	v_lshlrev_b32_e32 v2, 9, v0
	v_bitop3_b32 v153, s21, v3, v5 bitop3:0xf6
	v_and_b32_e32 v2, 0x30000, v2
	v_lshlrev_b32_e32 v3, 12, v15
	v_or3_b32 v2, v12, v2, v3
	v_add_u32_e32 v138, v2, v13
	v_lshlrev_b32_e32 v2, 5, v11
	s_waitcnt vmcnt(6)
	s_cmpk_lt_u32 s1, 0x100
	v_and_b32_e32 v2, 0x70000, v2
	s_cselect_b64 s[16:17], -1, 0
	v_or3_b32 v2, v12, v2, v3
	s_add_i32 s44, 0, 0x10000
	s_add_i32 s45, 0, 0x14000
	v_or_b32_e32 v155, s20, v14
	v_mov_b32_e32 v139, v135
	v_add_u32_e32 v140, v2, v13
	v_mov_b32_e32 v141, v135
	v_mov_b64_e32 v[142:143], 0x580
	v_mov_b64_e32 v[144:145], 0x57f
	v_add_u32_e32 v156, s44, v153
	v_add_u32_e32 v157, s45, v153
	v_add_u32_e32 v158, 0, v4
	s_movk_i32 s46, 0x2c00
	s_mov_b32 s47, 0
	s_barrier
	s_branch .LBB0_1101

;     __device__ __forceinline__ const char* aptr(const Unit& u) const { return (u.sub ? A2 : A) + (size_t)u.pm * tstep; }
;     __device__ __forceinline__ const char* bptr(const Unit& u) const { return (u.sub ? B2 : B) + (size_t)u.pn * tstep; }
;     __device__ __forceinline__ const char* aptr(const Unit& u) const { return (u.sub == 2 ? A2 : A + (size_t)u.sub * astride) + (size_t)u.pm * tstep; }
; #define PG8_STAGE(bufoff, gbase, voff) do { _Pragma("unroll") for (int _i = 0; _i < 2; ++_i) \
;         __builtin_amdgcn_global_load_lds((const unsigned*)((const char*)(gbase) + (voff)[_i]), (LAS unsigned*)(lds + (bufoff) + ldsw + _i * 8192), 16, 0, 0); } while (0)
; #define PG8_WAIT_V(n) asm volatile("s_waitcnt vmcnt(" #n ")" ::: "memory")
; #define PG8_BAR __builtin_amdgcn_s_barrier()
; #define PG8_STAGE(bufoff, gbase, voff) do { _Pragma("unroll") for (int _i = 0; _i < 2; ++_i) \
;         __builtin_amdgcn_global_load_lds((const unsigned*)((const char*)(gbase) + (voff)[_i]), (LAS unsigned*)(lds + (bufoff) + ldsw + _i * 8192), 16, 0, 0); } while (0)
; #define PG8_WAIT_V(n) asm volatile("s_waitcnt vmcnt(" #n ")" ::: "memory")
; #define PG8_BAR __builtin_amdgcn_s_barrier()
; template <class Epi, class Sched, bool ALIGN_EPI, bool SP2>
; __device__ __forceinline__ void gemm_phase(LAS unsigned char* lds, const int K, const Sched& S, const Epi& E) {
;     ...
;     Acc acc;
; #pragma unroll
;     for (int a = 0; a < 2; ++a)
; #pragma unroll
;         for (int b = 0; b < 2; ++b)
; #pragma unroll
;             for (int m = 0; m < 4; ++m)
; #pragma unroll
;                 for (int n = 0; n < 2; ++n) acc[a][b][m][n] = (f32x4){0.f, 0.f, 0.f, 0.f};
;     bf16x8 At[4][2], B0[2][2], B1[2][2];
;     const char* cA = S.aptr(cur); const char* cB = S.bptr(cur);
;     if constexpr (SP2) {
;         PG8_STAGE(PG8_SB(0, 0), cB, voffB); PG8_STAGE(PG8_SB(0, 1), cB + hstep, voffB); PG8_STAGE(PG8_SA(0, 0), cA, voffA); PG8_STAGE(PG8_SA(0, 1), cA + hstep, voffA);
;         if (wr == 1) PG8_BAR;
;         PG8_WAIT_V(2); PG8_BAR;
;         PG8_STAGE(PG8_SB(1, 0), cB + kstep, voffB); PG8_STAGE(PG8_SA(1, 0), cA + kstep, voffA); PG8_STAGE(PG8_SB(1, 1), cB + hstep + kstep, voffB);
;         PG8_WAIT_V(6); PG8_BAR;
.LBB0_1190:
	s_add_u32 s8, s34, 0xf800000
	s_addc_u32 s9, s35, 0
	s_lshl_b32 s5, s5, 5
	s_mov_b64 s[10:11], 0x80
	s_and_b32 s5, s5, 0x60
	s_add_i32 m0, s28, 0x18000
	v_lshl_add_u64 v[8:9], v[8:9], 0, s[10:11]
	s_lshl_b32 s16, s1, 13
	s_lshl_b32 s17, s5, 7
	global_load_lds_dwordx4 v[8:9], off
	v_lshl_add_u64 v[6:7], v[6:7], 0, s[10:11]
	s_add_i32 m0, s28, 0x1a000
	s_add_i32 s34, s28, 0x8000
	s_add_i32 s35, s28, 0xa000
	global_load_lds_dwordx4 v[6:7], off
	v_lshl_add_u64 v[2:3], v[2:3], 0, s[10:11]
	s_mov_b32 m0, s34
	s_add_u32 s12, s20, 0x160080
	global_load_lds_dwordx4 v[2:3], off
	v_lshl_add_u64 v[2:3], v[4:5], 0, s[10:11]
	s_mov_b32 m0, s35
	s_addc_u32 s13, s21, 0
	global_load_lds_dwordx4 v[2:3], off
	s_add_i32 m0, s28, 0x1c000
	v_lshl_add_u64 v[2:3], s[12:13], 0, v[130:131]
	global_load_lds_dwordx4 v[2:3], off
	v_lshl_add_u64 v[2:3], s[12:13], 0, v[134:135]
	s_add_i32 m0, s28, 0x1e000
	s_sext_i32_i8 s42, s0
	global_load_lds_dwordx4 v[2:3], off
	s_waitcnt vmcnt(8)
	s_barrier
	v_and_b32_e32 v2, 15, v0
	v_lshlrev_b32_e32 v3, 1, v11
	v_lshlrev_b32_e32 v4, 2, v0
	v_lshlrev_b32_e32 v0, 6, v0
	s_movk_i32 s0, 0x3c0
	v_and_b32_e32 v4, 32, v4
	v_and_or_b32 v0, v0, s0, v3
	v_lshl_or_b32 v152, s1, 6, v2
	v_lshl_or_b32 v2, v2, 6, v3
	v_bitop3_b32 v153, s17, v0, v4 bitop3:0xf6
	s_waitcnt vmcnt(6)
	s_cmpk_lt_u32 s4, 0x100
	v_add_u16_e32 v0, v1, v10
	v_bitop3_b32 v2, v2, s16, v4 bitop3:0xde
	s_cselect_b64 s[12:13], -1, 0
	v_lshrrev_b16_e32 v0, 1, v0
	s_add_i32 s37, 0, 0x10000
	s_add_i32 s38, 0, 0x14000
	s_ashr_i32 s36, s14, 31
	v_or_b32_e32 v154, s5, v11
	v_add_lshl_u32 v136, v12, v0, 1
	v_mov_b32_e32 v137, v131
	v_add_lshl_u32 v138, v13, v0, 1
	v_mov_b32_e32 v139, v131
	v_mov_b64_e32 v[140:141], 0x100
	v_mov_b64_e32 v[142:143], 0xff
	v_add_u32_e32 v155, s37, v153
	v_add_u32_e32 v156, s38, v153
	v_add_u32_e32 v157, 0, v2
	s_barrier
	s_branch .LBB0_1193
